# no s_setprio flips in GEMM loops + batched loads in prep_x / convert_T / B_MIX epilogue
# speedup vs baseline: 1.0069x; 1.0069x over previous
.LBB0_149:
	s_or_b64 exec, exec, s[0:1]
	s_lshl_b32 s0, s14, 7
	v_add_u32_e32 v22, s0, v82
	s_lshl_b32 s1, s13, 8
	v_ashrrev_i32_e32 v23, 31, v22
	v_readlane_b32 s14, v251, 9
	v_or_b32_e32 v0, s1, v81
	v_lshlrev_b64 v[2:3], 13, v[22:23]
	v_readlane_b32 s15, v251, 10
	v_lshlrev_b32_e32 v10, 2, v0
	v_lshlrev_b32_e32 v0, 1, v0
	v_lshl_add_u64 v[2:3], s[14:15], 0, v[2:3]
	v_lshl_add_u64 v[18:19], v[2:3], 0, v[0:1]
	s_movk_i32 s16, 0x1000
	v_readlane_b32 s52, v249, 13
	v_add_co_u32_e32 v18, vcc, s16, v18
	v_readlane_b32 s60, v249, 21
	v_readlane_b32 s61, v249, 22
	v_readlane_b32 s62, v249, 23
	v_readlane_b32 s63, v249, 24
	v_addc_co_u32_e32 v19, vcc, 0, v19, vcc
	s_waitcnt lgkmcnt(0)
	s_barrier
	global_load_dwordx4 v[6:9], v10, s[60:61]
	s_nop 0
	global_load_dwordx4 v[14:17], v10, s[62:63]
	global_load_dwordx4 v[2:5], v10, s[60:61] offset:16
	s_nop 0
	global_load_dwordx4 v[10:13], v10, s[62:63] offset:16
	s_add_i32 s2, 0, 0x1a800
	global_load_dwordx4 v[30:33], v[18:19], off
	v_add_u32_e32 v19, s2, v83
	v_add_u32_e32 v18, 16, v22
	ds_read_b64 v[38:39], v19
	v_ashrrev_i32_e32 v19, 31, v18
	v_lshlrev_b64 v[18:19], 13, v[18:19]
	v_lshl_add_u64 v[18:19], s[14:15], 0, v[18:19]
	v_lshl_add_u64 v[18:19], v[18:19], 0, v[0:1]
	v_add_co_u32_e32 v18, vcc, s16, v18
	v_add_u32_e32 v20, 32, v22
	s_nop 0
	v_addc_co_u32_e32 v19, vcc, 0, v19, vcc
	global_load_dwordx4 v[34:37], v[18:19], off
	v_add_u32_e32 v24, 48, v22
	v_ashrrev_i32_e32 v21, 31, v20
	v_ashrrev_i32_e32 v25, 31, v24
	v_add_u32_e32 v26, 64, v22
	v_add_u32_e32 v28, 0x50, v22
	v_lshlrev_b64 v[18:19], 13, v[20:21]
	v_lshlrev_b64 v[20:21], 13, v[24:25]
	v_ashrrev_i32_e32 v27, 31, v26
	v_ashrrev_i32_e32 v29, 31, v28
	v_lshl_add_u64 v[18:19], s[14:15], 0, v[18:19]
	v_lshl_add_u64 v[20:21], s[14:15], 0, v[20:21]
	v_lshlrev_b64 v[24:25], 13, v[26:27]
	v_lshlrev_b64 v[26:27], 13, v[28:29]
	v_lshl_add_u64 v[42:43], v[18:19], 0, v[0:1]
	v_lshl_add_u64 v[28:29], v[20:21], 0, v[0:1]
	v_lshl_add_u64 v[24:25], s[14:15], 0, v[24:25]
	v_lshl_add_u64 v[40:41], s[14:15], 0, v[26:27]
	v_lshl_add_u64 v[26:27], v[24:25], 0, v[0:1]
	v_lshl_add_u64 v[24:25], v[40:41], 0, v[0:1]
	s_mov_b32 s3, 0xffff0000
	v_readlane_b32 s53, v249, 14
	v_readlane_b32 s54, v249, 15
	v_readlane_b32 s55, v249, 16
	v_readlane_b32 s56, v249, 17
	v_readlane_b32 s57, v249, 18
	v_readlane_b32 s58, v249, 19
	v_readlane_b32 s59, v249, 20
	v_readlane_b32 s64, v249, 25
	v_readlane_b32 s65, v249, 26
	v_readlane_b32 s66, v249, 27
	v_readlane_b32 s67, v249, 28
	s_waitcnt vmcnt(0)
	v_mov_b32_e32 v18, v6
	v_mov_b32_e32 v19, v8
	s_waitcnt vmcnt(4)
	v_mov_b32_e32 v20, v14
	v_mov_b32_e32 v21, v16
	v_mov_b32_e32 v8, v7
	v_mov_b32_e32 v16, v15
	s_waitcnt vmcnt(3)
	v_mov_b32_e32 v6, v2
	v_mov_b32_e32 v7, v4
	s_waitcnt vmcnt(2)
	v_mov_b32_e32 v14, v10
	v_mov_b32_e32 v15, v12
	v_mov_b32_e32 v4, v3
	v_mov_b32_e32 v12, v11
	s_waitcnt vmcnt(1)
	v_lshlrev_b32_e32 v3, 16, v31
	v_lshlrev_b32_e32 v2, 16, v30
	v_and_b32_e32 v11, 0xffff0000, v31
	v_and_b32_e32 v10, 0xffff0000, v30
	v_lshlrev_b32_e32 v31, 16, v33
	v_lshlrev_b32_e32 v30, 16, v32
	v_and_b32_e32 v33, 0xffff0000, v33
	v_and_b32_e32 v32, 0xffff0000, v32
	s_waitcnt lgkmcnt(0)
	v_pk_add_f32 v[30:31], v[30:31], v[38:39] op_sel_hi:[1,0] neg_lo:[0,1] neg_hi:[0,1]
	v_pk_add_f32 v[2:3], v[2:3], v[38:39] op_sel_hi:[1,0] neg_lo:[0,1] neg_hi:[0,1]
	v_pk_add_f32 v[10:11], v[10:11], v[38:39] op_sel_hi:[1,0] neg_lo:[0,1] neg_hi:[0,1]
	v_pk_add_f32 v[32:33], v[32:33], v[38:39] op_sel_hi:[1,0] neg_lo:[0,1] neg_hi:[0,1]
	v_pk_mul_f32 v[30:31], v[30:31], v[38:39] op_sel:[0,1]
	v_pk_mul_f32 v[2:3], v[2:3], v[38:39] op_sel:[0,1]
	v_pk_mul_f32 v[10:11], v[10:11], v[38:39] op_sel:[0,1]
	v_pk_mul_f32 v[32:33], v[32:33], v[38:39] op_sel:[0,1]
	v_pk_fma_f32 v[38:39], v[6:7], v[30:31], v[14:15]
	v_add_co_u32_e32 v30, vcc, s16, v42
	v_pk_fma_f32 v[40:41], v[4:5], v[32:33], v[12:13]
	s_nop 0
	v_addc_co_u32_e32 v31, vcc, 0, v43, vcc
	global_load_dwordx4 v[30:33], v[30:31], off
	v_pk_fma_f32 v[2:3], v[18:19], v[2:3], v[20:21]
	v_bfe_u32 v23, v41, 16, 1
	v_bfe_u32 v44, v40, 16, 1
	v_pk_fma_f32 v[10:11], v[8:9], v[10:11], v[16:17]
	v_add3_u32 v40, v40, v44, s87
	v_add3_u32 v23, v41, v23, s87
	v_bfe_u32 v41, v2, 16, 1
	v_bfe_u32 v42, v3, 16, 1
	v_bfe_u32 v43, v38, 16, 1
	v_bfe_u32 v44, v39, 16, 1
	v_bfe_u32 v45, v11, 16, 1
	v_bfe_u32 v46, v10, 16, 1
	v_add3_u32 v39, v39, v44, s87
	v_add3_u32 v38, v38, v43, s87
	v_add3_u32 v3, v3, v42, s87
	v_add3_u32 v2, v2, v41, s87
	v_add3_u32 v10, v10, v46, s87
	v_add3_u32 v11, v11, v45, s87
	v_lshrrev_b32_e32 v2, 16, v2
	v_lshrrev_b32_e32 v3, 16, v3
	v_lshrrev_b32_e32 v38, 16, v38
	v_lshrrev_b32_e32 v39, 16, v39
	v_and_or_b32 v41, v23, s3, v39
	v_and_or_b32 v40, v40, s3, v38
	v_and_or_b32 v39, v11, s3, v3
	v_and_or_b32 v38, v10, s3, v2
	ds_write_b128 v96, v[38:41]
	v_add_u32_e32 v2, s2, v84
	ds_read_b64 v[2:3], v2
	s_waitcnt vmcnt(1)
	v_lshlrev_b32_e32 v39, 16, v35
	v_lshlrev_b32_e32 v38, 16, v34
	v_and_b32_e32 v35, 0xffff0000, v35
	v_and_b32_e32 v34, 0xffff0000, v34
	s_waitcnt lgkmcnt(0)
	v_pk_add_f32 v[34:35], v[34:35], v[2:3] op_sel_hi:[1,0] neg_lo:[0,1] neg_hi:[0,1]
	v_add_co_u32_e32 v28, vcc, s16, v28
	v_pk_mul_f32 v[34:35], v[34:35], v[2:3] op_sel:[0,1]
	v_pk_add_f32 v[38:39], v[38:39], v[2:3] op_sel_hi:[1,0] neg_lo:[0,1] neg_hi:[0,1]
	v_pk_fma_f32 v[40:41], v[8:9], v[34:35], v[16:17]
	v_lshlrev_b32_e32 v35, 16, v37
	v_lshlrev_b32_e32 v34, 16, v36
	v_pk_add_f32 v[34:35], v[34:35], v[2:3] op_sel_hi:[1,0] neg_lo:[0,1] neg_hi:[0,1]
	v_addc_co_u32_e32 v29, vcc, 0, v29, vcc
	v_pk_mul_f32 v[34:35], v[34:35], v[2:3] op_sel:[0,1]
	v_pk_mul_f32 v[38:39], v[38:39], v[2:3] op_sel:[0,1]
	v_pk_fma_f32 v[42:43], v[6:7], v[34:35], v[14:15]
	v_and_b32_e32 v35, 0xffff0000, v37
	v_and_b32_e32 v34, 0xffff0000, v36
	v_pk_add_f32 v[34:35], v[34:35], v[2:3] op_sel_hi:[1,0] neg_lo:[0,1] neg_hi:[0,1]
	v_pk_fma_f32 v[38:39], v[18:19], v[38:39], v[20:21]
	v_pk_mul_f32 v[2:3], v[34:35], v[2:3] op_sel:[0,1]
	global_load_dwordx4 v[34:37], v[28:29], off
	v_pk_fma_f32 v[2:3], v[4:5], v[2:3], v[12:13]
	v_bfe_u32 v45, v41, 16, 1
	v_bfe_u32 v23, v3, 16, 1
	v_bfe_u32 v44, v2, 16, 1
	v_bfe_u32 v46, v40, 16, 1
	v_add3_u32 v28, v40, v46, s87
	v_add3_u32 v29, v41, v45, s87
	v_add3_u32 v2, v2, v44, s87
	v_add3_u32 v3, v3, v23, s87
	v_bfe_u32 v23, v38, 16, 1
	v_bfe_u32 v40, v39, 16, 1
	v_bfe_u32 v41, v42, 16, 1
	v_bfe_u32 v44, v43, 16, 1
	v_add3_u32 v43, v43, v44, s87
	v_add3_u32 v41, v42, v41, s87
	v_add3_u32 v39, v39, v40, s87
	v_add3_u32 v23, v38, v23, s87
	v_lshrrev_b32_e32 v23, 16, v23
	v_lshrrev_b32_e32 v38, 16, v39
	v_lshrrev_b32_e32 v39, 16, v41
	v_lshrrev_b32_e32 v40, 16, v43
	v_and_or_b32 v41, v3, s3, v40
	v_and_or_b32 v40, v2, s3, v39
	v_and_or_b32 v39, v29, s3, v38
	v_and_or_b32 v38, v28, s3, v23
	ds_write_b128 v96, v[38:41] offset:9216
	v_add_u32_e32 v2, s2, v85
	ds_read_b64 v[2:3], v2
	s_waitcnt vmcnt(1)
	v_lshlrev_b32_e32 v29, 16, v31
	v_lshlrev_b32_e32 v28, 16, v30
	v_add_co_u32_e32 v26, vcc, s16, v26
	s_waitcnt lgkmcnt(0)
	v_pk_add_f32 v[28:29], v[28:29], v[2:3] op_sel_hi:[1,0] neg_lo:[0,1] neg_hi:[0,1]
	v_addc_co_u32_e32 v27, vcc, 0, v27, vcc
	v_pk_mul_f32 v[28:29], v[28:29], v[2:3] op_sel:[0,1]
	v_add_u32_e32 v10, 0x60, v22
	v_pk_fma_f32 v[38:39], v[18:19], v[28:29], v[20:21]
	v_and_b32_e32 v29, 0xffff0000, v31
	v_and_b32_e32 v28, 0xffff0000, v30
	v_pk_add_f32 v[28:29], v[28:29], v[2:3] op_sel_hi:[1,0] neg_lo:[0,1] neg_hi:[0,1]
	v_ashrrev_i32_e32 v11, 31, v10
	v_pk_mul_f32 v[28:29], v[28:29], v[2:3] op_sel:[0,1]
	v_lshlrev_b64 v[10:11], 13, v[10:11]
	v_pk_fma_f32 v[30:31], v[8:9], v[28:29], v[16:17]
	v_lshlrev_b32_e32 v29, 16, v33
	v_lshlrev_b32_e32 v28, 16, v32
	v_pk_add_f32 v[28:29], v[28:29], v[2:3] op_sel_hi:[1,0] neg_lo:[0,1] neg_hi:[0,1]
	v_bfe_u32 v42, v30, 16, 1
	v_pk_mul_f32 v[28:29], v[28:29], v[2:3] op_sel:[0,1]
	v_add3_u32 v30, v30, v42, s87
	v_pk_fma_f32 v[40:41], v[6:7], v[28:29], v[14:15]
	v_and_b32_e32 v29, 0xffff0000, v33
	v_and_b32_e32 v28, 0xffff0000, v32
	v_pk_add_f32 v[28:29], v[28:29], v[2:3] op_sel_hi:[1,0] neg_lo:[0,1] neg_hi:[0,1]
	v_bfe_u32 v33, v31, 16, 1
	v_pk_mul_f32 v[2:3], v[28:29], v[2:3] op_sel:[0,1]
	v_add3_u32 v31, v31, v33, s87
	v_pk_fma_f32 v[2:3], v[4:5], v[2:3], v[12:13]
	v_bfe_u32 v33, v40, 16, 1
	v_bfe_u32 v23, v3, 16, 1
	v_bfe_u32 v32, v2, 16, 1
	v_add3_u32 v2, v2, v32, s87
	v_add3_u32 v3, v3, v23, s87
	v_bfe_u32 v23, v38, 16, 1
	v_bfe_u32 v32, v39, 16, 1
	v_bfe_u32 v42, v41, 16, 1
	v_add3_u32 v41, v41, v42, s87
	v_add3_u32 v33, v40, v33, s87
	v_add3_u32 v32, v39, v32, s87
	v_add3_u32 v23, v38, v23, s87
	global_load_dwordx4 v[26:29], v[26:27], off
	v_lshrrev_b32_e32 v23, 16, v23
	v_lshrrev_b32_e32 v38, 16, v32
	v_lshrrev_b32_e32 v32, 16, v33
	v_lshrrev_b32_e32 v33, 16, v41
	v_and_or_b32 v33, v3, s3, v33
	v_and_or_b32 v32, v2, s3, v32
	v_and_or_b32 v31, v31, s3, v38
	v_and_or_b32 v30, v30, s3, v23
	ds_write_b128 v96, v[30:33] offset:18432
	v_add_u32_e32 v2, s2, v86
	ds_read_b64 v[2:3], v2
	v_add_u32_e32 v38, 0x70, v22
	s_waitcnt vmcnt(1)
	v_lshlrev_b32_e32 v23, 16, v35
	v_lshlrev_b32_e32 v22, 16, v34
	v_lshl_add_u64 v[10:11], s[14:15], 0, v[10:11]
	s_waitcnt lgkmcnt(0)
	v_pk_add_f32 v[22:23], v[22:23], v[2:3] op_sel_hi:[1,0] neg_lo:[0,1] neg_hi:[0,1]
	v_lshl_add_u64 v[10:11], v[10:11], 0, v[0:1]
	v_pk_mul_f32 v[22:23], v[22:23], v[2:3] op_sel:[0,1]
	s_nop 0
	v_pk_fma_f32 v[30:31], v[18:19], v[22:23], v[20:21]
	v_and_b32_e32 v23, 0xffff0000, v35
	v_and_b32_e32 v22, 0xffff0000, v34
	v_pk_add_f32 v[22:23], v[22:23], v[2:3] op_sel_hi:[1,0] neg_lo:[0,1] neg_hi:[0,1]
	s_nop 0
	v_pk_mul_f32 v[22:23], v[22:23], v[2:3] op_sel:[0,1]
	s_nop 0
	v_pk_fma_f32 v[32:33], v[8:9], v[22:23], v[16:17]
	v_lshlrev_b32_e32 v23, 16, v37
	v_lshlrev_b32_e32 v22, 16, v36
	v_pk_add_f32 v[22:23], v[22:23], v[2:3] op_sel_hi:[1,0] neg_lo:[0,1] neg_hi:[0,1]
	v_bfe_u32 v39, v33, 16, 1
	v_pk_mul_f32 v[22:23], v[22:23], v[2:3] op_sel:[0,1]
	v_bfe_u32 v40, v32, 16, 1
	v_pk_fma_f32 v[34:35], v[6:7], v[22:23], v[14:15]
	v_and_b32_e32 v23, 0xffff0000, v37
	v_and_b32_e32 v22, 0xffff0000, v36
	v_pk_add_f32 v[22:23], v[22:23], v[2:3] op_sel_hi:[1,0] neg_lo:[0,1] neg_hi:[0,1]
	v_add3_u32 v40, v32, v40, s87
	v_pk_mul_f32 v[2:3], v[22:23], v[2:3] op_sel:[0,1]
	v_add_co_u32_e32 v22, vcc, s16, v24
	v_pk_fma_f32 v[2:3], v[4:5], v[2:3], v[12:13]
	s_nop 0
	v_addc_co_u32_e32 v23, vcc, 0, v25, vcc
	global_load_dwordx4 v[22:25], v[22:23], off
	v_bfe_u32 v36, v3, 16, 1
	v_bfe_u32 v37, v2, 16, 1
	v_add3_u32 v39, v33, v39, s87
	v_add3_u32 v2, v2, v37, s87
	v_add3_u32 v3, v3, v36, s87
	v_bfe_u32 v32, v30, 16, 1
	v_bfe_u32 v33, v31, 16, 1
	v_bfe_u32 v36, v34, 16, 1
	v_bfe_u32 v37, v35, 16, 1
	v_add3_u32 v35, v35, v37, s87
	v_add3_u32 v34, v34, v36, s87
	v_add3_u32 v31, v31, v33, s87
	v_add3_u32 v30, v30, v32, s87
	v_lshrrev_b32_e32 v30, 16, v30
	v_lshrrev_b32_e32 v31, 16, v31
	v_lshrrev_b32_e32 v32, 16, v34
	v_lshrrev_b32_e32 v33, 16, v35
	v_and_or_b32 v33, v3, s3, v33
	v_and_or_b32 v32, v2, s3, v32
	v_and_or_b32 v31, v39, s3, v31
	v_and_or_b32 v30, v40, s3, v30
	ds_write_b128 v96, v[30:33] offset:27648
	v_add_u32_e32 v2, s2, v87
	ds_read_b64 v[2:3], v2
	v_ashrrev_i32_e32 v39, 31, v38
	v_add_co_u32_e32 v10, vcc, s16, v10
	v_lshlrev_b64 v[34:35], 13, v[38:39]
	s_nop 0
	v_addc_co_u32_e32 v11, vcc, 0, v11, vcc
	s_waitcnt vmcnt(1)
	v_lshlrev_b32_e32 v31, 16, v27
	v_lshlrev_b32_e32 v30, 16, v26
	v_and_b32_e32 v27, 0xffff0000, v27
	v_and_b32_e32 v26, 0xffff0000, v26
	s_waitcnt lgkmcnt(0)
	v_pk_add_f32 v[26:27], v[26:27], v[2:3] op_sel_hi:[1,0] neg_lo:[0,1] neg_hi:[0,1]
	v_pk_add_f32 v[30:31], v[30:31], v[2:3] op_sel_hi:[1,0] neg_lo:[0,1] neg_hi:[0,1]
	v_pk_mul_f32 v[26:27], v[26:27], v[2:3] op_sel:[0,1]
	v_pk_mul_f32 v[30:31], v[30:31], v[2:3] op_sel:[0,1]
	v_pk_fma_f32 v[32:33], v[8:9], v[26:27], v[16:17]
	v_lshlrev_b32_e32 v27, 16, v29
	v_lshlrev_b32_e32 v26, 16, v28
	v_pk_add_f32 v[26:27], v[26:27], v[2:3] op_sel_hi:[1,0] neg_lo:[0,1] neg_hi:[0,1]
	v_pk_fma_f32 v[30:31], v[18:19], v[30:31], v[20:21]
	v_pk_mul_f32 v[26:27], v[26:27], v[2:3] op_sel:[0,1]
	v_bfe_u32 v40, v33, 16, 1
	v_pk_fma_f32 v[36:37], v[6:7], v[26:27], v[14:15]
	v_and_b32_e32 v27, 0xffff0000, v29
	v_and_b32_e32 v26, 0xffff0000, v28
	v_pk_add_f32 v[26:27], v[26:27], v[2:3] op_sel_hi:[1,0] neg_lo:[0,1] neg_hi:[0,1]
	v_bfe_u32 v41, v32, 16, 1
	v_pk_mul_f32 v[2:3], v[26:27], v[2:3] op_sel:[0,1]
	global_load_dwordx4 v[26:29], v[10:11], off
	v_pk_fma_f32 v[2:3], v[4:5], v[2:3], v[12:13]
	v_add3_u32 v10, v32, v41, s87
	v_bfe_u32 v38, v3, 16, 1
	v_bfe_u32 v39, v2, 16, 1
	v_add3_u32 v11, v33, v40, s87
	v_add3_u32 v2, v2, v39, s87
	v_add3_u32 v3, v3, v38, s87
	v_bfe_u32 v32, v30, 16, 1
	v_bfe_u32 v33, v31, 16, 1
	v_bfe_u32 v38, v36, 16, 1
	v_bfe_u32 v39, v37, 16, 1
	v_add3_u32 v37, v37, v39, s87
	v_add3_u32 v36, v36, v38, s87
	v_add3_u32 v31, v31, v33, s87
	v_add3_u32 v30, v30, v32, s87
	v_lshrrev_b32_e32 v30, 16, v30
	v_lshrrev_b32_e32 v31, 16, v31
	v_lshrrev_b32_e32 v32, 16, v36
	v_lshrrev_b32_e32 v33, 16, v37
	v_and_or_b32 v33, v3, s3, v33
	v_and_or_b32 v32, v2, s3, v32
	v_and_or_b32 v31, v11, s3, v31
	v_and_or_b32 v30, v10, s3, v30
	ds_write_b128 v96, v[30:33] offset:36864
	v_add_u32_e32 v2, s2, v88
	ds_read_b64 v[2:3], v2
	s_waitcnt vmcnt(1)
	v_lshlrev_b32_e32 v31, 16, v23
	v_lshlrev_b32_e32 v30, 16, v22
	v_and_b32_e32 v23, 0xffff0000, v23
	v_and_b32_e32 v22, 0xffff0000, v22
	s_waitcnt lgkmcnt(0)
	v_pk_add_f32 v[22:23], v[22:23], v[2:3] op_sel_hi:[1,0] neg_lo:[0,1] neg_hi:[0,1]
	v_lshl_add_u64 v[10:11], s[14:15], 0, v[34:35]
	v_pk_mul_f32 v[22:23], v[22:23], v[2:3] op_sel:[0,1]
	v_lshl_add_u64 v[10:11], v[10:11], 0, v[0:1]
	v_pk_fma_f32 v[32:33], v[8:9], v[22:23], v[16:17]
	v_lshlrev_b32_e32 v23, 16, v25
	v_lshlrev_b32_e32 v22, 16, v24
	v_pk_add_f32 v[22:23], v[22:23], v[2:3] op_sel_hi:[1,0] neg_lo:[0,1] neg_hi:[0,1]
	v_add_co_u32_e32 v10, vcc, s16, v10
	v_pk_mul_f32 v[22:23], v[22:23], v[2:3] op_sel:[0,1]
	v_pk_add_f32 v[30:31], v[30:31], v[2:3] op_sel_hi:[1,0] neg_lo:[0,1] neg_hi:[0,1]
	v_pk_fma_f32 v[34:35], v[6:7], v[22:23], v[14:15]
	v_and_b32_e32 v23, 0xffff0000, v25
	v_and_b32_e32 v22, 0xffff0000, v24
	v_pk_add_f32 v[22:23], v[22:23], v[2:3] op_sel_hi:[1,0] neg_lo:[0,1] neg_hi:[0,1]
	v_addc_co_u32_e32 v11, vcc, 0, v11, vcc
	v_pk_mul_f32 v[30:31], v[30:31], v[2:3] op_sel:[0,1]
	v_pk_mul_f32 v[2:3], v[22:23], v[2:3] op_sel:[0,1]
	global_load_dwordx4 v[22:25], v[10:11], off
	v_pk_fma_f32 v[2:3], v[4:5], v[2:3], v[12:13]
	v_pk_fma_f32 v[30:31], v[18:19], v[30:31], v[20:21]
	v_bfe_u32 v0, v3, 16, 1
	v_bfe_u32 v10, v2, 16, 1
	v_bfe_u32 v11, v33, 16, 1
	v_bfe_u32 v36, v32, 16, 1
	v_add3_u32 v36, v32, v36, s87
	v_add3_u32 v11, v33, v11, s87
	v_add3_u32 v2, v2, v10, s87
	v_add3_u32 v0, v3, v0, s87
	v_bfe_u32 v3, v30, 16, 1
	v_bfe_u32 v10, v31, 16, 1
	v_bfe_u32 v32, v34, 16, 1
	v_bfe_u32 v33, v35, 16, 1
	v_add3_u32 v33, v35, v33, s87
	v_add3_u32 v32, v34, v32, s87
	v_add3_u32 v10, v31, v10, s87
	v_add3_u32 v3, v30, v3, s87
	v_lshrrev_b32_e32 v3, 16, v3
	v_lshrrev_b32_e32 v10, 16, v10
	v_lshrrev_b32_e32 v30, 16, v32
	v_lshrrev_b32_e32 v31, 16, v33
	v_and_or_b32 v33, v0, s3, v31
	v_and_or_b32 v32, v2, s3, v30
	v_and_or_b32 v31, v11, s3, v10
	v_and_or_b32 v30, v36, s3, v3
	ds_write_b128 v96, v[30:33] offset:46080
	v_add_u32_e32 v0, s2, v89
	ds_read_b64 v[2:3], v0
	s_waitcnt vmcnt(1)
	v_lshlrev_b32_e32 v11, 16, v27
	v_lshlrev_b32_e32 v10, 16, v26
	v_and_b32_e32 v27, 0xffff0000, v27
	v_and_b32_e32 v26, 0xffff0000, v26
	v_lshlrev_b32_e32 v31, 16, v29
	v_lshlrev_b32_e32 v30, 16, v28
	v_and_b32_e32 v29, 0xffff0000, v29
	v_and_b32_e32 v28, 0xffff0000, v28
	s_waitcnt lgkmcnt(0)
	v_pk_add_f32 v[10:11], v[10:11], v[2:3] op_sel_hi:[1,0] neg_lo:[0,1] neg_hi:[0,1]
	v_pk_add_f32 v[26:27], v[26:27], v[2:3] op_sel_hi:[1,0] neg_lo:[0,1] neg_hi:[0,1]
	v_pk_add_f32 v[30:31], v[30:31], v[2:3] op_sel_hi:[1,0] neg_lo:[0,1] neg_hi:[0,1]
	v_pk_add_f32 v[28:29], v[28:29], v[2:3] op_sel_hi:[1,0] neg_lo:[0,1] neg_hi:[0,1]
	v_pk_mul_f32 v[10:11], v[10:11], v[2:3] op_sel:[0,1]
	v_pk_mul_f32 v[26:27], v[26:27], v[2:3] op_sel:[0,1]
	v_pk_mul_f32 v[30:31], v[30:31], v[2:3] op_sel:[0,1]
	v_pk_mul_f32 v[2:3], v[28:29], v[2:3] op_sel:[0,1]
	v_pk_fma_f32 v[26:27], v[8:9], v[26:27], v[16:17]
	v_pk_fma_f32 v[2:3], v[4:5], v[2:3], v[12:13]
	v_pk_fma_f32 v[10:11], v[18:19], v[10:11], v[20:21]
	v_pk_fma_f32 v[30:31], v[6:7], v[30:31], v[14:15]
	v_bfe_u32 v0, v3, 16, 1
	v_bfe_u32 v28, v2, 16, 1
	v_bfe_u32 v29, v27, 16, 1
	v_bfe_u32 v32, v26, 16, 1
	v_add3_u32 v26, v26, v32, s87
	v_add3_u32 v27, v27, v29, s87
	v_add3_u32 v2, v2, v28, s87
	v_add3_u32 v0, v3, v0, s87
	v_bfe_u32 v3, v10, 16, 1
	v_bfe_u32 v28, v11, 16, 1
	v_bfe_u32 v29, v30, 16, 1
	v_bfe_u32 v32, v31, 16, 1
	v_add3_u32 v31, v31, v32, s87
	v_add3_u32 v29, v30, v29, s87
	v_add3_u32 v11, v11, v28, s87
	v_add3_u32 v3, v10, v3, s87
	v_lshrrev_b32_e32 v3, 16, v3
	v_lshrrev_b32_e32 v10, 16, v11
	v_lshrrev_b32_e32 v11, 16, v29
	v_lshrrev_b32_e32 v28, 16, v31
	v_and_or_b32 v29, v0, s3, v28
	v_and_or_b32 v28, v2, s3, v11
	v_and_or_b32 v27, v27, s3, v10
	v_and_or_b32 v26, v26, s3, v3
	ds_write_b128 v96, v[26:29] offset:55296
	v_add_u32_e32 v0, s2, v90
	ds_read_b64 v[2:3], v0
	s_movk_i32 s2, 0xff00
	s_waitcnt vmcnt(0)
	v_lshlrev_b32_e32 v11, 16, v23
	v_lshlrev_b32_e32 v10, 16, v22
	s_waitcnt lgkmcnt(0)
	v_pk_add_f32 v[10:11], v[10:11], v[2:3] op_sel_hi:[1,0] neg_lo:[0,1] neg_hi:[0,1]
	s_nop 0
	v_pk_mul_f32 v[10:11], v[10:11], v[2:3] op_sel:[0,1]
	s_nop 0
	v_pk_fma_f32 v[10:11], v[18:19], v[10:11], v[20:21]
	v_and_b32_e32 v19, 0xffff0000, v23
	v_and_b32_e32 v18, 0xffff0000, v22
	v_pk_add_f32 v[18:19], v[18:19], v[2:3] op_sel_hi:[1,0] neg_lo:[0,1] neg_hi:[0,1]
	s_nop 0
	v_pk_mul_f32 v[18:19], v[18:19], v[2:3] op_sel:[0,1]
	s_nop 0
	v_pk_fma_f32 v[8:9], v[8:9], v[18:19], v[16:17]
	v_lshlrev_b32_e32 v17, 16, v25
	v_lshlrev_b32_e32 v16, 16, v24
	v_pk_add_f32 v[16:17], v[16:17], v[2:3] op_sel_hi:[1,0] neg_lo:[0,1] neg_hi:[0,1]
	s_nop 0
	v_pk_mul_f32 v[16:17], v[16:17], v[2:3] op_sel:[0,1]
	s_nop 0
	v_pk_fma_f32 v[6:7], v[6:7], v[16:17], v[14:15]
	v_and_b32_e32 v15, 0xffff0000, v25
	v_and_b32_e32 v14, 0xffff0000, v24
	v_pk_add_f32 v[14:15], v[14:15], v[2:3] op_sel_hi:[1,0] neg_lo:[0,1] neg_hi:[0,1]
	s_nop 0
	v_pk_mul_f32 v[2:3], v[14:15], v[2:3] op_sel:[0,1]
	s_nop 0
	v_pk_fma_f32 v[2:3], v[4:5], v[2:3], v[12:13]
	v_bfe_u32 v5, v9, 16, 1
	v_bfe_u32 v0, v3, 16, 1
	v_bfe_u32 v4, v2, 16, 1
	v_bfe_u32 v12, v8, 16, 1
	v_add3_u32 v8, v8, v12, s87
	v_add3_u32 v9, v9, v5, s87
	v_add3_u32 v2, v2, v4, s87
	v_add3_u32 v0, v3, v0, s87
	v_bfe_u32 v3, v10, 16, 1
	v_bfe_u32 v4, v11, 16, 1
	v_bfe_u32 v5, v6, 16, 1
	v_bfe_u32 v12, v7, 16, 1
	v_add3_u32 v7, v7, v12, s87
	v_add3_u32 v5, v6, v5, s87
	v_add3_u32 v4, v11, v4, s87
	v_add3_u32 v3, v10, v3, s87
	v_lshrrev_b32_e32 v6, 16, v3
	v_lshrrev_b32_e32 v3, 16, v4
	v_lshrrev_b32_e32 v4, 16, v5
	v_lshrrev_b32_e32 v5, 16, v7
	v_and_or_b32 v5, v0, s3, v5
	v_and_or_b32 v4, v2, s3, v4
	v_and_or_b32 v3, v9, s3, v3
	v_and_or_b32 v2, v8, s3, v6
	ds_write_b128 v96, v[2:5] offset:64512
	v_mov_b32_e32 v2, 0
	v_mov_b32_e32 v0, v95
	v_mov_b32_e32 v3, v2
	v_mov_b32_e32 v4, v2
	v_mov_b32_e32 v5, v2
	v_mov_b32_e32 v6, v2
	v_mov_b32_e32 v7, v2
	v_mov_b32_e32 v8, v2
	v_mov_b32_e32 v9, v2
	v_mov_b32_e32 v10, v2
	v_mov_b32_e32 v11, v2
	v_mov_b32_e32 v12, v2
	v_mov_b32_e32 v13, v2
	v_mov_b32_e32 v14, v2
	v_mov_b32_e32 v15, v2
	v_mov_b32_e32 v16, v2
	v_mov_b32_e32 v17, v2
	v_mov_b32_e32 v18, v2
	v_mov_b32_e32 v19, v2
	v_mov_b32_e32 v20, v2
	v_mov_b32_e32 v21, v2
	v_mov_b32_e32 v22, v2
	v_mov_b32_e32 v23, v2
	v_mov_b32_e32 v24, v2
	v_mov_b32_e32 v25, v2
	v_mov_b32_e32 v26, v2
	v_mov_b32_e32 v27, v2
	v_mov_b32_e32 v28, v2
	v_mov_b32_e32 v29, v2
	v_mov_b32_e32 v30, v2
	v_mov_b32_e32 v31, v2
	v_mov_b32_e32 v32, v2
	v_mov_b32_e32 v33, v2
	v_mov_b32_e32 v34, v2
	v_mov_b32_e32 v35, v2
	v_mov_b32_e32 v36, v2
	v_mov_b32_e32 v37, v2
	v_mov_b32_e32 v38, v2
	v_mov_b32_e32 v39, v2
	v_mov_b32_e32 v40, v2
	v_mov_b32_e32 v41, v2
	v_mov_b32_e32 v42, v2
	v_mov_b32_e32 v43, v2
	v_mov_b32_e32 v44, v2
	v_mov_b32_e32 v45, v2
	v_mov_b32_e32 v46, v2
	v_mov_b32_e32 v47, v2
	v_mov_b32_e32 v48, v2
	v_mov_b32_e32 v49, v2
	v_mov_b32_e32 v50, v2
	v_mov_b32_e32 v51, v2
	v_mov_b32_e32 v52, v2
	v_mov_b32_e32 v53, v2
	v_mov_b32_e32 v54, v2
	v_mov_b32_e32 v55, v2
	v_mov_b32_e32 v56, v2
	v_mov_b32_e32 v57, v2
	v_mov_b32_e32 v58, v2
	v_mov_b32_e32 v59, v2
	v_mov_b32_e32 v60, v2
	v_mov_b32_e32 v61, v2
	v_mov_b32_e32 v62, v2
	v_mov_b32_e32 v63, v2
	v_mov_b32_e32 v64, v2
	v_mov_b32_e32 v65, v2
	s_lshl_b32 s80, s1, 1
	v_readlane_b32 s66, v249, 27
	v_readlane_b32 s67, v249, 28
	v_lshl_add_u64 v[196:197], v[66:67], 0, s[80:81]
	v_lshlrev_b32_e32 v198, 2, v79
	v_lshl_or_b32 v198, s13, 9, v198
	v_or_b32_e32 v200, s0, v79
	v_ashrrev_i32_e32 v201, 31, v200
	v_lshlrev_b64 v[200:201], 13, v[200:201]
	v_lshl_add_u64 v[200:201], v[196:197], 0, v[200:201]
	global_load_dwordx2 v[160:161], v[200:201], off
	global_load_dwordx2 v[162:163], v[200:201], off offset:16
	global_load_dwordx2 v[164:165], v[200:201], off offset:32
	global_load_dwordx2 v[166:167], v[200:201], off offset:48
	global_load_dword v192, v198, s[66:67]
	v_or_b32_e32 v200, s0, v91
	v_ashrrev_i32_e32 v201, 31, v200
	v_lshlrev_b64 v[200:201], 13, v[200:201]
	v_lshl_add_u64 v[200:201], v[196:197], 0, v[200:201]
	global_load_dwordx2 v[168:169], v[200:201], off
	global_load_dwordx2 v[170:171], v[200:201], off offset:16
	global_load_dwordx2 v[172:173], v[200:201], off offset:32
	global_load_dwordx2 v[174:175], v[200:201], off offset:48
	global_load_dword v193, v198, s[66:67] offset:128
	v_or_b32_e32 v200, s0, v92
	v_ashrrev_i32_e32 v201, 31, v200
	v_lshlrev_b64 v[200:201], 13, v[200:201]
	v_lshl_add_u64 v[200:201], v[196:197], 0, v[200:201]
	global_load_dwordx2 v[176:177], v[200:201], off
	global_load_dwordx2 v[178:179], v[200:201], off offset:16
	global_load_dwordx2 v[180:181], v[200:201], off offset:32
	global_load_dwordx2 v[182:183], v[200:201], off offset:48
	global_load_dword v194, v198, s[66:67] offset:256
	v_or_b32_e32 v200, s0, v93
	v_ashrrev_i32_e32 v201, 31, v200
	v_lshlrev_b64 v[200:201], 13, v[200:201]
	v_lshl_add_u64 v[200:201], v[196:197], 0, v[200:201]
	global_load_dwordx2 v[184:185], v[200:201], off
	global_load_dwordx2 v[186:187], v[200:201], off offset:16
	global_load_dwordx2 v[188:189], v[200:201], off offset:32
	global_load_dwordx2 v[190:191], v[200:201], off offset:48
	global_load_dword v195, v198, s[66:67] offset:384
	s_waitcnt lgkmcnt(0)
	s_barrier
.LBB0_150:
	v_add_u32_e32 v74, 0xffffdc00, v0
	v_add_u32_e32 v97, s2, v94
	v_add_u32_e32 v75, 0xffffe500, v0
	ds_read_b64_tr_b16 v[70:71], v74
	ds_read_b64_tr_b16 v[72:73], v75
	s_waitcnt lgkmcnt(0)
	v_add_u32_e32 v74, 0x12100, v97
	ds_read_b128 v[74:77], v74
	s_add_i32 s2, s2, 64
	s_waitcnt lgkmcnt(0)
	v_mfma_f32_32x32x16_bf16 v[50:65], v[70:73], v[74:77], v[50:65]
	v_add_u32_e32 v74, 0x14300, v97
	ds_read_b128 v[74:77], v74
	s_cmp_eq_u32 s2, 0
	s_waitcnt lgkmcnt(0)
	v_mfma_f32_32x32x16_bf16 v[34:49], v[70:73], v[74:77], v[34:49]
	v_add_u32_e32 v74, 0x16500, v97
	ds_read_b128 v[74:77], v74
	s_waitcnt lgkmcnt(0)
	v_mfma_f32_32x32x16_bf16 v[18:33], v[70:73], v[74:77], v[18:33]
	v_add_u32_e32 v74, 0x18700, v97
	ds_read_b128 v[74:77], v74
	s_waitcnt lgkmcnt(0)
	v_mfma_f32_32x32x16_bf16 v[2:17], v[70:73], v[74:77], v[2:17]
	v_add_u32_e32 v74, 0x900, v0
	ds_read_b64_tr_b16 v[70:71], v0
	ds_read_b64_tr_b16 v[72:73], v74
	s_waitcnt lgkmcnt(0)
	v_add_u32_e32 v74, 0x12120, v97
	ds_read_b128 v[74:77], v74
	v_add_u32_e32 v0, 0x4800, v0
	s_waitcnt lgkmcnt(0)
	v_mfma_f32_32x32x16_bf16 v[50:65], v[70:73], v[74:77], v[50:65]
	v_add_u32_e32 v74, 0x14320, v97
	ds_read_b128 v[74:77], v74
	s_waitcnt lgkmcnt(0)
	v_mfma_f32_32x32x16_bf16 v[34:49], v[70:73], v[74:77], v[34:49]
	v_add_u32_e32 v74, 0x16520, v97
	ds_read_b128 v[74:77], v74
	s_waitcnt lgkmcnt(0)
	v_mfma_f32_32x32x16_bf16 v[18:33], v[70:73], v[74:77], v[18:33]
	v_add_u32_e32 v74, 0x18720, v97
	ds_read_b128 v[74:77], v74
	s_waitcnt lgkmcnt(0)
	v_mfma_f32_32x32x16_bf16 v[2:17], v[70:73], v[74:77], v[2:17]
	s_cbranch_scc0 .LBB0_150
	s_waitcnt vmcnt(0)
	v_or_b32_e32 v74, s0, v79
	s_lshl_b32 s80, s1, 1
	v_ashrrev_i32_e32 v75, 31, v74
	v_lshl_add_u64 v[72:73], v[66:67], 0, s[80:81]
	v_lshlrev_b32_e32 v0, 2, v79
	v_readlane_b32 s52, v249, 13
	v_lshlrev_b64 v[76:77], 13, v[74:75]
	v_lshl_or_b32 v0, s13, 9, v0
	v_readlane_b32 s66, v249, 27
	v_readlane_b32 s67, v249, 28
	v_lshl_add_u64 v[76:77], v[72:73], 0, v[76:77]
	v_mov_b64_e32 v[98:99], v[160:161]
	v_lshl_add_u64 v[70:71], v[68:69], 0, s[80:81]
	v_lshlrev_b64 v[74:75], 12, v[74:75]
	v_lshl_add_u64 v[74:75], v[70:71], 0, v[74:75]
	v_mov_b32_e32 v97, v192
	v_readlane_b32 s60, v249, 21
	v_readlane_b32 s61, v249, 22
	s_add_i32 s12, s12, s34
	s_cmpk_gt_i32 s12, 0x3ff
	v_readlane_b32 s23, v249, 41
	v_readlane_b32 s60, v248, 31
	v_readlane_b32 s53, v249, 14
	v_readlane_b32 s54, v249, 15
	v_readlane_b32 s55, v249, 16
	v_readlane_b32 s56, v249, 17
	v_readlane_b32 s57, v249, 18
	v_readlane_b32 s58, v249, 19
	v_readlane_b32 s59, v249, 20
	v_readlane_b32 s62, v249, 23
	v_readlane_b32 s63, v249, 24
	v_readlane_b32 s64, v249, 25
	v_readlane_b32 s65, v249, 26
	v_readlane_b32 s61, v248, 32
	v_lshlrev_b32_e32 v100, 16, v98
	v_and_b32_e32 v98, 0xffff0000, v98
	v_add_f32_e32 v50, v50, v97
	v_add_f32_e32 v51, v51, v97
	v_mul_f32_e32 v50, v50, v100
	v_mul_f32_e32 v51, v51, v98
	v_cvt_pk_bf16_f32 v50, v50, v51
	v_lshlrev_b32_e32 v51, 16, v99
	v_add_f32_e32 v52, v52, v97
	v_mul_f32_e32 v51, v52, v51
	v_and_b32_e32 v52, 0xffff0000, v99
	v_add_f32_e32 v53, v53, v97
	v_mul_f32_e32 v52, v53, v52
	v_cvt_pk_bf16_f32 v51, v51, v52
	global_store_dwordx2 v[74:75], v[50:51], off
	v_mov_b64_e32 v[50:51], v[162:163]
	v_add_f32_e32 v53, v54, v97
	v_lshlrev_b32_e32 v52, 16, v50
	v_mul_f32_e32 v52, v53, v52
	v_and_b32_e32 v50, 0xffff0000, v50
	v_add_f32_e32 v53, v55, v97
	v_mul_f32_e32 v50, v53, v50
	v_cvt_pk_bf16_f32 v50, v52, v50
	v_lshlrev_b32_e32 v52, 16, v51
	v_add_f32_e32 v53, v56, v97
	v_mul_f32_e32 v52, v53, v52
	v_and_b32_e32 v51, 0xffff0000, v51
	v_add_f32_e32 v53, v57, v97
	v_mul_f32_e32 v51, v53, v51
	v_cvt_pk_bf16_f32 v51, v52, v51
	global_store_dwordx2 v[74:75], v[50:51], off offset:16
	v_mov_b64_e32 v[50:51], v[164:165]
	v_add_f32_e32 v53, v58, v97
	v_lshlrev_b32_e32 v52, 16, v50
	v_mul_f32_e32 v52, v53, v52
	v_and_b32_e32 v50, 0xffff0000, v50
	v_add_f32_e32 v53, v59, v97
	v_mul_f32_e32 v50, v53, v50
	v_cvt_pk_bf16_f32 v50, v52, v50
	v_lshlrev_b32_e32 v52, 16, v51
	v_add_f32_e32 v53, v60, v97
	v_mul_f32_e32 v52, v53, v52
	v_and_b32_e32 v51, 0xffff0000, v51
	v_add_f32_e32 v53, v61, v97
	v_mul_f32_e32 v51, v53, v51
	v_cvt_pk_bf16_f32 v51, v52, v51
	global_store_dwordx2 v[74:75], v[50:51], off offset:32
	v_mov_b64_e32 v[50:51], v[166:167]
	v_add_f32_e32 v53, v62, v97
	v_lshlrev_b32_e32 v52, 16, v50
	v_mul_f32_e32 v52, v53, v52
	v_and_b32_e32 v50, 0xffff0000, v50
	v_add_f32_e32 v53, v63, v97
	v_mul_f32_e32 v50, v53, v50
	v_cvt_pk_bf16_f32 v50, v52, v50
	v_lshlrev_b32_e32 v52, 16, v51
	v_add_f32_e32 v53, v64, v97
	v_mul_f32_e32 v52, v53, v52
	v_and_b32_e32 v51, 0xffff0000, v51
	v_add_f32_e32 v53, v65, v97
	v_mul_f32_e32 v51, v53, v51
	v_cvt_pk_bf16_f32 v51, v52, v51
	global_store_dwordx2 v[74:75], v[50:51], off offset:48
	v_or_b32_e32 v50, s0, v91
	v_ashrrev_i32_e32 v51, 31, v50
	v_lshlrev_b64 v[52:53], 13, v[50:51]
	v_lshl_add_u64 v[52:53], v[72:73], 0, v[52:53]
	v_mov_b32_e32 v56, v193
	v_mov_b64_e32 v[54:55], v[168:169]
	v_lshlrev_b64 v[50:51], 12, v[50:51]
	v_lshl_add_u64 v[50:51], v[70:71], 0, v[50:51]
	v_add_f32_e32 v34, v34, v56
	v_lshlrev_b32_e32 v57, 16, v54
	v_and_b32_e32 v54, 0xffff0000, v54
	v_add_f32_e32 v35, v35, v56
	v_mul_f32_e32 v34, v34, v57
	v_mul_f32_e32 v35, v35, v54
	v_cvt_pk_bf16_f32 v34, v34, v35
	v_lshlrev_b32_e32 v35, 16, v55
	v_add_f32_e32 v36, v36, v56
	v_mul_f32_e32 v35, v36, v35
	v_and_b32_e32 v36, 0xffff0000, v55
	v_add_f32_e32 v37, v37, v56
	v_mul_f32_e32 v36, v37, v36
	v_cvt_pk_bf16_f32 v35, v35, v36
	global_store_dwordx2 v[50:51], v[34:35], off
	v_mov_b64_e32 v[34:35], v[170:171]
	v_add_f32_e32 v37, v38, v56
	v_lshlrev_b32_e32 v36, 16, v34
	v_mul_f32_e32 v36, v37, v36
	v_and_b32_e32 v34, 0xffff0000, v34
	v_add_f32_e32 v37, v39, v56
	v_mul_f32_e32 v34, v37, v34
	v_cvt_pk_bf16_f32 v34, v36, v34
	v_lshlrev_b32_e32 v36, 16, v35
	v_add_f32_e32 v37, v40, v56
	v_mul_f32_e32 v36, v37, v36
	v_and_b32_e32 v35, 0xffff0000, v35
	v_add_f32_e32 v37, v41, v56
	v_mul_f32_e32 v35, v37, v35
	v_cvt_pk_bf16_f32 v35, v36, v35
	global_store_dwordx2 v[50:51], v[34:35], off offset:16
	v_mov_b64_e32 v[34:35], v[172:173]
	v_add_f32_e32 v37, v42, v56
	v_lshlrev_b32_e32 v36, 16, v34
	v_mul_f32_e32 v36, v37, v36
	v_and_b32_e32 v34, 0xffff0000, v34
	v_add_f32_e32 v37, v43, v56
	v_mul_f32_e32 v34, v37, v34
	v_cvt_pk_bf16_f32 v34, v36, v34
	v_lshlrev_b32_e32 v36, 16, v35
	v_add_f32_e32 v37, v44, v56
	v_mul_f32_e32 v36, v37, v36
	v_and_b32_e32 v35, 0xffff0000, v35
	v_add_f32_e32 v37, v45, v56
	v_mul_f32_e32 v35, v37, v35
	v_cvt_pk_bf16_f32 v35, v36, v35
	global_store_dwordx2 v[50:51], v[34:35], off offset:32
	v_mov_b64_e32 v[34:35], v[174:175]
	v_add_f32_e32 v37, v46, v56
	v_lshlrev_b32_e32 v36, 16, v34
	v_mul_f32_e32 v36, v37, v36
	v_and_b32_e32 v34, 0xffff0000, v34
	v_add_f32_e32 v37, v47, v56
	v_mul_f32_e32 v34, v37, v34
	v_cvt_pk_bf16_f32 v34, v36, v34
	v_lshlrev_b32_e32 v36, 16, v35
	v_add_f32_e32 v37, v48, v56
	v_mul_f32_e32 v36, v37, v36
	v_and_b32_e32 v35, 0xffff0000, v35
	v_add_f32_e32 v37, v49, v56
	v_mul_f32_e32 v35, v37, v35
	v_cvt_pk_bf16_f32 v35, v36, v35
	global_store_dwordx2 v[50:51], v[34:35], off offset:48
	v_or_b32_e32 v34, s0, v92
	v_ashrrev_i32_e32 v35, 31, v34
	v_lshlrev_b64 v[36:37], 13, v[34:35]
	v_lshl_add_u64 v[36:37], v[72:73], 0, v[36:37]
	v_mov_b32_e32 v40, v194
	v_mov_b64_e32 v[38:39], v[176:177]
	v_lshlrev_b64 v[34:35], 12, v[34:35]
	v_lshl_add_u64 v[34:35], v[70:71], 0, v[34:35]
	v_add_f32_e32 v18, v18, v40
	v_lshlrev_b32_e32 v41, 16, v38
	v_and_b32_e32 v38, 0xffff0000, v38
	v_add_f32_e32 v19, v19, v40
	v_mul_f32_e32 v18, v18, v41
	v_mul_f32_e32 v19, v19, v38
	v_cvt_pk_bf16_f32 v18, v18, v19
	v_lshlrev_b32_e32 v19, 16, v39
	v_add_f32_e32 v20, v20, v40
	v_mul_f32_e32 v19, v20, v19
	v_and_b32_e32 v20, 0xffff0000, v39
	v_add_f32_e32 v21, v21, v40
	v_mul_f32_e32 v20, v21, v20
	v_cvt_pk_bf16_f32 v19, v19, v20
	global_store_dwordx2 v[34:35], v[18:19], off
	v_mov_b64_e32 v[18:19], v[178:179]
	v_add_f32_e32 v21, v22, v40
	v_lshlrev_b32_e32 v20, 16, v18
	v_mul_f32_e32 v20, v21, v20
	v_and_b32_e32 v18, 0xffff0000, v18
	v_add_f32_e32 v21, v23, v40
	v_mul_f32_e32 v18, v21, v18
	v_cvt_pk_bf16_f32 v18, v20, v18
	v_lshlrev_b32_e32 v20, 16, v19
	v_add_f32_e32 v21, v24, v40
	v_mul_f32_e32 v20, v21, v20
	v_and_b32_e32 v19, 0xffff0000, v19
	v_add_f32_e32 v21, v25, v40
	v_mul_f32_e32 v19, v21, v19
	v_cvt_pk_bf16_f32 v19, v20, v19
	global_store_dwordx2 v[34:35], v[18:19], off offset:16
	v_mov_b64_e32 v[18:19], v[180:181]
	v_add_f32_e32 v21, v26, v40
	v_lshlrev_b32_e32 v20, 16, v18
	v_mul_f32_e32 v20, v21, v20
	v_and_b32_e32 v18, 0xffff0000, v18
	v_add_f32_e32 v21, v27, v40
	v_mul_f32_e32 v18, v21, v18
	v_cvt_pk_bf16_f32 v18, v20, v18
	v_lshlrev_b32_e32 v20, 16, v19
	v_add_f32_e32 v21, v28, v40
	v_mul_f32_e32 v20, v21, v20
	v_and_b32_e32 v19, 0xffff0000, v19
	v_add_f32_e32 v21, v29, v40
	v_mul_f32_e32 v19, v21, v19
	v_cvt_pk_bf16_f32 v19, v20, v19
	global_store_dwordx2 v[34:35], v[18:19], off offset:32
	v_mov_b64_e32 v[18:19], v[182:183]
	v_add_f32_e32 v21, v30, v40
	v_lshlrev_b32_e32 v20, 16, v18
	v_mul_f32_e32 v20, v21, v20
	v_and_b32_e32 v18, 0xffff0000, v18
	v_add_f32_e32 v21, v31, v40
	v_mul_f32_e32 v18, v21, v18
	v_cvt_pk_bf16_f32 v18, v20, v18
	v_lshlrev_b32_e32 v20, 16, v19
	v_add_f32_e32 v21, v32, v40
	v_mul_f32_e32 v20, v21, v20
	v_and_b32_e32 v19, 0xffff0000, v19
	v_add_f32_e32 v21, v33, v40
	v_mul_f32_e32 v19, v21, v19
	v_cvt_pk_bf16_f32 v19, v20, v19
	global_store_dwordx2 v[34:35], v[18:19], off offset:48
	v_or_b32_e32 v18, s0, v93
	v_ashrrev_i32_e32 v19, 31, v18
	v_lshlrev_b64 v[20:21], 13, v[18:19]
	v_lshl_add_u64 v[20:21], v[72:73], 0, v[20:21]
	v_mov_b32_e32 v0, v195
	v_lshlrev_b64 v[18:19], 12, v[18:19]
	v_mov_b64_e32 v[22:23], v[184:185]
	v_lshl_add_u64 v[18:19], v[70:71], 0, v[18:19]
	v_add_f32_e32 v2, v2, v0
	v_add_f32_e32 v3, v3, v0
	v_lshlrev_b32_e32 v24, 16, v22
	v_and_b32_e32 v22, 0xffff0000, v22
	v_mul_f32_e32 v2, v2, v24
	v_mul_f32_e32 v3, v3, v22
	v_cvt_pk_bf16_f32 v2, v2, v3
	v_lshlrev_b32_e32 v3, 16, v23
	v_add_f32_e32 v4, v4, v0
	v_mul_f32_e32 v3, v4, v3
	v_and_b32_e32 v4, 0xffff0000, v23
	v_add_f32_e32 v5, v5, v0
	v_mul_f32_e32 v4, v5, v4
	v_cvt_pk_bf16_f32 v3, v3, v4
	global_store_dwordx2 v[18:19], v[2:3], off
	v_mov_b64_e32 v[2:3], v[186:187]
	v_add_f32_e32 v5, v6, v0
	v_lshlrev_b32_e32 v4, 16, v2
	v_mul_f32_e32 v4, v5, v4
	v_and_b32_e32 v2, 0xffff0000, v2
	v_add_f32_e32 v5, v7, v0
	v_mul_f32_e32 v2, v5, v2
	v_cvt_pk_bf16_f32 v2, v4, v2
	v_lshlrev_b32_e32 v4, 16, v3
	v_add_f32_e32 v5, v8, v0
	v_mul_f32_e32 v4, v5, v4
	v_and_b32_e32 v3, 0xffff0000, v3
	v_add_f32_e32 v5, v9, v0
	v_mul_f32_e32 v3, v5, v3
	v_cvt_pk_bf16_f32 v3, v4, v3
	global_store_dwordx2 v[18:19], v[2:3], off offset:16
	v_mov_b64_e32 v[2:3], v[188:189]
	v_add_f32_e32 v5, v10, v0
	v_lshlrev_b32_e32 v4, 16, v2
	v_mul_f32_e32 v4, v5, v4
	v_and_b32_e32 v2, 0xffff0000, v2
	v_add_f32_e32 v5, v11, v0
	v_mul_f32_e32 v2, v5, v2
	v_cvt_pk_bf16_f32 v2, v4, v2
	v_lshlrev_b32_e32 v4, 16, v3
	v_add_f32_e32 v5, v12, v0
	v_mul_f32_e32 v4, v5, v4
	v_and_b32_e32 v3, 0xffff0000, v3
	v_add_f32_e32 v5, v13, v0
	v_mul_f32_e32 v3, v5, v3
	v_cvt_pk_bf16_f32 v3, v4, v3
	global_store_dwordx2 v[18:19], v[2:3], off offset:32
	v_mov_b64_e32 v[2:3], v[190:191]
	v_add_f32_e32 v5, v14, v0
	v_lshlrev_b32_e32 v4, 16, v2
	v_mul_f32_e32 v4, v5, v4
	v_and_b32_e32 v2, 0xffff0000, v2
	v_add_f32_e32 v5, v15, v0
	v_mul_f32_e32 v2, v5, v2
	v_cvt_pk_bf16_f32 v2, v4, v2
	v_lshlrev_b32_e32 v4, 16, v3
	v_add_f32_e32 v5, v16, v0
	v_and_b32_e32 v3, 0xffff0000, v3
	v_add_f32_e32 v0, v17, v0
	v_mul_f32_e32 v4, v5, v4
	v_mul_f32_e32 v0, v0, v3
	v_cvt_pk_bf16_f32 v3, v4, v0
	global_store_dwordx2 v[18:19], v[2:3], off offset:48
	s_cbranch_scc0 .LBB0_144

.LBB0_469:
	v_ashrrev_i32_e32 v9, 4, v8
	v_add_u32_e32 v10, s2, v9
	v_ashrrev_i32_e32 v11, 31, v10
	v_lshlrev_b64 v[10:11], 12, v[10:11]
	v_lshlrev_b32_e32 v0, 2, v3
	v_lshl_add_u64 v[10:11], s[10:11], 0, v[10:11]
	v_and_b32_e32 v0, 0xf0, v0
	v_lshl_add_u64 v[10:11], v[10:11], 0, v[0:1]
	global_load_dwordx4 v[10:13], v[10:11], off
	v_mul_lo_u32 v9, v9, s27
	v_add3_u32 v0, 0, v9, v0
	v_add_u32_e32 v3, 0x800, v3
	v_add_u32_e32 v168, 0x200, v8
	v_mov_b32_e32 v161, 0
	v_ashrrev_i32_e32 v169, 4, v168
	v_add_u32_e32 v170, s2, v169
	v_ashrrev_i32_e32 v171, 31, v170
	v_lshlrev_b64 v[170:171], 12, v[170:171]
	v_lshlrev_b32_e32 v160, 2, v3
	v_lshl_add_u64 v[170:171], s[10:11], 0, v[170:171]
	v_and_b32_e32 v160, 0xf0, v160
	v_lshl_add_u64 v[170:171], v[170:171], 0, v[160:161]
	global_load_dwordx4 v[170:173], v[170:171], off
	v_mul_lo_u32 v169, v169, s27
	v_add3_u32 v160, 0, v169, v160
	v_add_u32_e32 v3, 0x800, v3
	s_waitcnt vmcnt(0)
	ds_write2_b32 v0, v10, v11 offset1:1
	ds_write2_b32 v0, v12, v13 offset0:2 offset1:3
	ds_write2_b32 v160, v170, v171 offset1:1
	ds_write2_b32 v160, v172, v173 offset0:2 offset1:3
	s_branch .LBB0_466

.LBB0_487:
	v_ashrrev_i32_e32 v9, 4, v8
	v_add_u32_e32 v10, s2, v9
	v_ashrrev_i32_e32 v11, 31, v10
	v_lshlrev_b64 v[10:11], 12, v[10:11]
	v_lshlrev_b32_e32 v0, 2, v3
	v_lshl_add_u64 v[10:11], s[8:9], 0, v[10:11]
	v_and_b32_e32 v0, 0xf0, v0
	v_lshl_add_u64 v[10:11], v[10:11], 0, v[0:1]
	global_load_dwordx4 v[10:13], v[10:11], off
	v_mul_lo_u32 v9, v9, s27
	v_add3_u32 v0, 0, v9, v0
	v_add_u32_e32 v3, 0x800, v3
	v_add_u32_e32 v168, 0x200, v8
	v_mov_b32_e32 v161, 0
	v_ashrrev_i32_e32 v169, 4, v168
	v_add_u32_e32 v170, s2, v169
	v_ashrrev_i32_e32 v171, 31, v170
	v_lshlrev_b64 v[170:171], 12, v[170:171]
	v_lshlrev_b32_e32 v160, 2, v3
	v_lshl_add_u64 v[170:171], s[8:9], 0, v[170:171]
	v_and_b32_e32 v160, 0xf0, v160
	v_lshl_add_u64 v[170:171], v[170:171], 0, v[160:161]
	global_load_dwordx4 v[170:173], v[170:171], off
	v_mul_lo_u32 v169, v169, s27
	v_add3_u32 v160, 0, v169, v160
	v_add_u32_e32 v3, 0x800, v3
	s_waitcnt vmcnt(0)
	ds_write2_b32 v0, v10, v11 offset1:1
	ds_write2_b32 v0, v12, v13 offset0:2 offset1:3
	ds_write2_b32 v160, v170, v171 offset1:1
	ds_write2_b32 v160, v172, v173 offset0:2 offset1:3
	s_branch .LBB0_484

.LBB0_523:
	v_ashrrev_i32_e32 v9, 4, v8
	v_add_u32_e32 v10, s2, v9
	v_ashrrev_i32_e32 v11, 31, v10
	v_lshlrev_b64 v[12:13], 14, v[10:11]
	v_lshlrev_b32_e32 v0, 2, v3
	v_lshl_add_u64 v[12:13], s[10:11], 0, v[12:13]
	v_and_b32_e32 v0, 0xf0, v0
	v_lshl_add_u64 v[12:13], v[12:13], 0, v[0:1]
	v_lshl_add_u64 v[10:11], v[10:11], 2, s[16:17]
	global_load_dword v14, v[10:11], off
	v_mul_lo_u32 v9, v9, s27
	global_load_dwordx4 v[10:13], v[12:13], off
	v_add3_u32 v0, 0, v9, v0
	v_add_u32_e32 v3, 0x800, v3
	v_add_u32_e32 v168, 0x200, v8
	v_mov_b32_e32 v161, 0
	v_ashrrev_i32_e32 v169, 4, v168
	v_add_u32_e32 v170, s2, v169
	v_ashrrev_i32_e32 v171, 31, v170
	v_lshlrev_b64 v[172:173], 14, v[170:171]
	v_lshlrev_b32_e32 v160, 2, v3
	v_lshl_add_u64 v[172:173], s[10:11], 0, v[172:173]
	v_and_b32_e32 v160, 0xf0, v160
	v_lshl_add_u64 v[172:173], v[172:173], 0, v[160:161]
	v_lshl_add_u64 v[170:171], v[170:171], 2, s[16:17]
	global_load_dword v174, v[170:171], off
	v_mul_lo_u32 v169, v169, s27
	global_load_dwordx4 v[170:173], v[172:173], off
	v_add3_u32 v160, 0, v169, v160
	v_add_u32_e32 v3, 0x800, v3
	s_waitcnt vmcnt(0)
	v_pk_mul_f32 v[10:11], v[10:11], v[14:15] op_sel_hi:[1,0]
	ds_write2_b32 v0, v10, v11 offset1:1
	v_pk_mul_f32 v[10:11], v[12:13], v[14:15] op_sel_hi:[1,0]
	ds_write2_b32 v0, v10, v11 offset0:2 offset1:3
	v_pk_mul_f32 v[170:171], v[170:171], v[174:175] op_sel_hi:[1,0]
	ds_write2_b32 v160, v170, v171 offset1:1
	v_pk_mul_f32 v[170:171], v[172:173], v[174:175] op_sel_hi:[1,0]
	ds_write2_b32 v160, v170, v171 offset0:2 offset1:3
	s_branch .LBB0_520

.LBB0_535:
	v_ashrrev_i32_e32 v9, 4, v8
	v_add_u32_e32 v10, s2, v9
	v_mov_b64_e32 v[12:13], s[10:11]
	s_movk_i32 s0, 0x4800
	v_lshlrev_b32_e32 v0, 2, v3
	v_ashrrev_i32_e32 v11, 31, v10
	v_mad_i64_i32 v[12:13], s[0:1], v10, s0, v[12:13]
	v_and_b32_e32 v0, 0xf0, v0
	v_lshl_add_u64 v[12:13], v[12:13], 0, v[0:1]
	v_lshl_add_u64 v[10:11], v[10:11], 2, s[16:17]
	global_load_dword v14, v[10:11], off
	v_mul_lo_u32 v9, v9, s27
	global_load_dwordx4 v[10:13], v[12:13], off
	v_add3_u32 v0, 0, v9, v0
	v_add_u32_e32 v3, 0x800, v3
	v_add_u32_e32 v168, 0x200, v8
	v_mov_b32_e32 v161, 0
	v_ashrrev_i32_e32 v169, 4, v168
	v_add_u32_e32 v170, s2, v169
	v_mov_b64_e32 v[172:173], s[10:11]
	s_movk_i32 s0, 0x4800
	v_lshlrev_b32_e32 v160, 2, v3
	v_ashrrev_i32_e32 v171, 31, v170
	v_mad_i64_i32 v[172:173], s[0:1], v170, s0, v[172:173]
	v_and_b32_e32 v160, 0xf0, v160
	v_lshl_add_u64 v[172:173], v[172:173], 0, v[160:161]
	v_lshl_add_u64 v[170:171], v[170:171], 2, s[16:17]
	global_load_dword v174, v[170:171], off
	v_mul_lo_u32 v169, v169, s27
	global_load_dwordx4 v[170:173], v[172:173], off
	v_add3_u32 v160, 0, v169, v160
	v_add_u32_e32 v3, 0x800, v3
	s_waitcnt vmcnt(0)
	v_pk_mul_f32 v[10:11], v[10:11], v[14:15] op_sel_hi:[1,0]
	ds_write2_b32 v0, v10, v11 offset1:1
	v_pk_mul_f32 v[10:11], v[12:13], v[14:15] op_sel_hi:[1,0]
	ds_write2_b32 v0, v10, v11 offset0:2 offset1:3
	v_pk_mul_f32 v[170:171], v[170:171], v[174:175] op_sel_hi:[1,0]
	ds_write2_b32 v160, v170, v171 offset1:1
	v_pk_mul_f32 v[170:171], v[172:173], v[174:175] op_sel_hi:[1,0]
	ds_write2_b32 v160, v170, v171 offset0:2 offset1:3
	s_branch .LBB0_532

.LBB0_548:
	v_cmp_lt_i32_e64 s[0:1], s87, v2
	v_mov_b64_e32 v[10:11], v[2:3]
	s_waitcnt lgkmcnt(0)
	v_mov_b64_e32 v[12:13], v[8:9]
	s_and_saveexec_b64 s[8:9], s[0:1]
	v_add_u32_e32 v10, 0xffff8000, v2
	v_mov_b32_e32 v11, v1
	v_lshlrev_b64 v[10:11], 12, v[10:11]
	v_lshl_add_u64 v[12:13], s[38:39], 0, v[10:11]
	v_mov_b32_e32 v10, v2
	v_mov_b32_e32 v11, v1
	s_or_b64 exec, exec, s[8:9]
	v_lshl_add_u64 v[14:15], v[12:13], 0, v[0:1]
	v_lshlrev_b64 v[12:13], 11, v[10:11]
	v_lshl_add_u64 v[12:13], v[4:5], 0, v[12:13]
	global_load_dwordx4 v[22:25], v[14:15], off
	global_load_dwordx4 v[30:33], v[14:15], off offset:1024
	global_load_dwordx4 v[34:37], v[14:15], off offset:2048
	global_load_dwordx4 v[38:41], v[14:15], off offset:3072
	s_waitcnt vmcnt(3)
	v_mul_f32_e32 v26, v23, v23
	v_fmac_f32_e32 v26, v22, v22
	v_and_b32_sdwa v27, v24, v152 dst_sel:DWORD dst_unused:UNUSED_PAD src0_sel:WORD_1 src1_sel:DWORD
	v_and_b32_sdwa v28, v22, v152 dst_sel:DWORD dst_unused:UNUSED_PAD src0_sel:WORD_1 src1_sel:DWORD
	v_fmac_f32_e32 v26, v24, v24
	v_add3_u32 v22, v22, v28, s87
	v_add3_u32 v24, v24, v27, s87
	v_and_b32_sdwa v27, v25, v152 dst_sel:DWORD dst_unused:UNUSED_PAD src0_sel:WORD_1 src1_sel:DWORD
	v_and_b32_sdwa v28, v23, v152 dst_sel:DWORD dst_unused:UNUSED_PAD src0_sel:WORD_1 src1_sel:DWORD
	v_fmac_f32_e32 v26, v25, v25
	v_add3_u32 v25, v25, v27, s87
	v_add3_u32 v23, v23, v28, s87
	v_and_b32_e32 v25, 0xffff0000, v25
	v_and_b32_e32 v27, 0xffff0000, v23
	v_or_b32_sdwa v23, v25, v24 dst_sel:DWORD dst_unused:UNUSED_PAD src0_sel:DWORD src1_sel:WORD_1
	v_or_b32_sdwa v22, v27, v22 dst_sel:DWORD dst_unused:UNUSED_PAD src0_sel:DWORD src1_sel:WORD_1
	global_store_dwordx2 v[12:13], v[22:23], off
	s_waitcnt vmcnt(3)
	v_mul_f32_e32 v27, v31, v31
	v_fmac_f32_e32 v27, v30, v30
	v_fmac_f32_e32 v27, v32, v32
	v_fmac_f32_e32 v27, v33, v33
	v_add_f32_e32 v26, v26, v27
	v_and_b32_sdwa v27, v32, v152 dst_sel:DWORD dst_unused:UNUSED_PAD src0_sel:WORD_1 src1_sel:DWORD
	v_and_b32_sdwa v28, v30, v152 dst_sel:DWORD dst_unused:UNUSED_PAD src0_sel:WORD_1 src1_sel:DWORD
	v_add3_u32 v30, v30, v28, s87
	v_add3_u32 v32, v32, v27, s87
	v_and_b32_sdwa v27, v33, v152 dst_sel:DWORD dst_unused:UNUSED_PAD src0_sel:WORD_1 src1_sel:DWORD
	v_and_b32_sdwa v28, v31, v152 dst_sel:DWORD dst_unused:UNUSED_PAD src0_sel:WORD_1 src1_sel:DWORD
	v_add3_u32 v33, v33, v27, s87
	v_add3_u32 v31, v31, v28, s87
	v_and_b32_e32 v33, 0xffff0000, v33
	v_and_b32_e32 v27, 0xffff0000, v31
	v_or_b32_sdwa v31, v33, v32 dst_sel:DWORD dst_unused:UNUSED_PAD src0_sel:DWORD src1_sel:WORD_1
	v_or_b32_sdwa v30, v27, v30 dst_sel:DWORD dst_unused:UNUSED_PAD src0_sel:DWORD src1_sel:WORD_1
	global_store_dwordx2 v[12:13], v[30:31], off offset:512
	s_waitcnt vmcnt(3)
	v_mul_f32_e32 v27, v35, v35
	v_fmac_f32_e32 v27, v34, v34
	v_fmac_f32_e32 v27, v36, v36
	v_fmac_f32_e32 v27, v37, v37
	v_add_f32_e32 v26, v26, v27
	v_and_b32_sdwa v27, v36, v152 dst_sel:DWORD dst_unused:UNUSED_PAD src0_sel:WORD_1 src1_sel:DWORD
	v_and_b32_sdwa v28, v34, v152 dst_sel:DWORD dst_unused:UNUSED_PAD src0_sel:WORD_1 src1_sel:DWORD
	v_add3_u32 v34, v34, v28, s87
	v_add3_u32 v36, v36, v27, s87
	v_and_b32_sdwa v27, v37, v152 dst_sel:DWORD dst_unused:UNUSED_PAD src0_sel:WORD_1 src1_sel:DWORD
	v_and_b32_sdwa v28, v35, v152 dst_sel:DWORD dst_unused:UNUSED_PAD src0_sel:WORD_1 src1_sel:DWORD
	v_add3_u32 v37, v37, v27, s87
	v_add3_u32 v35, v35, v28, s87
	v_and_b32_e32 v37, 0xffff0000, v37
	v_and_b32_e32 v27, 0xffff0000, v35
	v_or_b32_sdwa v35, v37, v36 dst_sel:DWORD dst_unused:UNUSED_PAD src0_sel:DWORD src1_sel:WORD_1
	v_or_b32_sdwa v34, v27, v34 dst_sel:DWORD dst_unused:UNUSED_PAD src0_sel:DWORD src1_sel:WORD_1
	global_store_dwordx2 v[12:13], v[34:35], off offset:1024
	s_waitcnt vmcnt(3)
	v_mul_f32_e32 v14, v39, v39
	v_fmac_f32_e32 v14, v38, v38
	v_fmac_f32_e32 v14, v40, v40
	v_fmac_f32_e32 v14, v41, v41
	v_add_f32_e32 v26, v26, v14
	v_and_b32_sdwa v14, v40, v152 dst_sel:DWORD dst_unused:UNUSED_PAD src0_sel:WORD_1 src1_sel:DWORD
	v_and_b32_sdwa v15, v38, v152 dst_sel:DWORD dst_unused:UNUSED_PAD src0_sel:WORD_1 src1_sel:DWORD
	v_add3_u32 v38, v38, v15, s87
	v_add3_u32 v14, v40, v14, s87
	v_and_b32_sdwa v15, v41, v152 dst_sel:DWORD dst_unused:UNUSED_PAD src0_sel:WORD_1 src1_sel:DWORD
	v_and_b32_sdwa v40, v39, v152 dst_sel:DWORD dst_unused:UNUSED_PAD src0_sel:WORD_1 src1_sel:DWORD
	v_add3_u32 v15, v41, v15, s87
	v_add3_u32 v39, v39, v40, s87
	v_and_b32_e32 v15, 0xffff0000, v15
	v_and_b32_e32 v39, 0xffff0000, v39
	v_or_b32_sdwa v15, v15, v14 dst_sel:DWORD dst_unused:UNUSED_PAD src0_sel:DWORD src1_sel:WORD_1
	v_or_b32_sdwa v14, v39, v38 dst_sel:DWORD dst_unused:UNUSED_PAD src0_sel:DWORD src1_sel:WORD_1
	global_store_dwordx2 v[12:13], v[14:15], off offset:1536
	ds_bpermute_b32 v12, v16, v26
	s_waitcnt lgkmcnt(0)
	v_add_f32_e32 v12, v26, v12
	ds_bpermute_b32 v13, v17, v12
	s_waitcnt lgkmcnt(0)
	v_add_f32_e32 v12, v12, v13
	ds_bpermute_b32 v13, v18, v12
	s_waitcnt lgkmcnt(0)
	v_add_f32_e32 v12, v12, v13
	ds_bpermute_b32 v13, v19, v12
	s_waitcnt lgkmcnt(0)
	v_add_f32_e32 v12, v12, v13
	ds_bpermute_b32 v13, v20, v12
	s_waitcnt lgkmcnt(0)
	v_add_f32_e32 v12, v12, v13
	ds_bpermute_b32 v13, v21, v12
	s_and_saveexec_b64 s[0:1], vcc
	s_cbranch_execz .LBB0_547
	s_waitcnt lgkmcnt(0)
	v_add_f32_e32 v12, v12, v13
	v_cndmask_b32_e64 v12, 0, v12, s[4:5]
	v_lshl_add_u64 v[10:11], v[10:11], 4, v[6:7]
	global_store_dword v[10:11], v12, off
	s_branch .LBB0_547
